# plus P2 sub-phase order swapped for half the workgroups (conv+pool before FFT stage 1) so HBM-bound and LDS/VALU-bound work overlap across CUs
# speedup vs baseline: 1.0109x; 1.0086x over previous
; #define LAS __attribute__((address_space(3)))
; __global__ void __launch_bounds__(512, 2) fwd_megakernel(Params p_) {
;     ...
;         if (PHM & 8)
;         {
;             TID_VARS
;             KARGS
;             { LAS float* WD0 = (LAS float*)lds; const float* wdw = p->in[I_WDW] + (size_t)l * 31 * 512;
;               for (int e = tid; e < 31 * 512; e += 512) WD0[e] = wdw[e]; }
.LBB0_291:
	s_or_b64 exec, exec, s[38:39]
	v_readlane_b32 s0, v253, 0
	v_mov_b32_e32 v48, v246
	v_readlane_b32 s1, v253, 1
	s_waitcnt lgkmcnt(0)
	s_barrier
	v_readlane_b32 s101, v253, 7
	s_nop 0
	s_bfe_u32 s101, s101, 0x10003
	s_movk_i32 s2, 0x3e00
	v_writelane_b32 v255, s0, 10
	s_load_dwordx2 s[6:7], s[0:1], 0xd0
	v_ashrrev_i32_e32 v49, 31, v48
	v_writelane_b32 v255, s1, 11
	v_readfirstlane_b32 s0, v48
	v_cmp_gt_i32_e32 vcc, s2, v48
	s_nop 0
	v_writelane_b32 v255, s0, 12
	s_and_saveexec_b64 s[8:9], vcc
	s_cbranch_execz .LBB0_306
	v_readlane_b32 s0, v255, 10
	v_readlane_b32 s1, v255, 11
	s_load_dwordx2 s[10:11], s[0:1], 0x68
	v_max_i32_e32 v0, 0x3c00, v48
	v_sub_u32_e32 v0, v0, v48
	v_add_u32_e32 v1, 0x1ff, v0
	s_movk_i32 s2, 0x1ff
	v_cmp_lt_u32_e32 vcc, s2, v1
	s_mov_b64 s[4:5], -1
	v_mov_b32_e32 v0, v48
	v_mov_b64_e32 v[2:3], v[48:49]
	s_and_saveexec_b64 s[12:13], vcc
	s_cbranch_execz .LBB0_303
	v_lshrrev_b32_e32 v2, 9, v1
	v_readlane_b32 s0, v255, 6
	s_mul_i32 s3, s0, 0xf800
	v_add_u32_e32 v4, -1, v2
	s_mul_hi_u32 s2, s0, 0xf800
	s_waitcnt lgkmcnt(0)
	s_add_u32 s14, s10, s3
	v_lshrrev_b32_e32 v3, 1, v4
	s_addc_u32 s15, s11, s2
	v_add_u32_e32 v1, 0x200, v48
	v_mov_b32_e32 v0, v48
	v_add_u32_e32 v3, 1, v3
	v_cmp_lt_u32_e32 vcc, 13, v4
	v_mov_b32_e32 v6, 0
	v_readlane_b32 s1, v255, 7
	s_and_saveexec_b64 s[16:17], vcc
	s_cbranch_execz .LBB0_297
	v_and_b32_e32 v4, -8, v3
	v_lshl_add_u32 v5, v48, 2, 0
	s_mov_b32 s2, 0
	s_mov_b64 s[18:19], 0

; __global__ void __launch_bounds__(512, 2) fwd_megakernel(Params p_) {
;     ...
;             for (int t = bid; t < 1024; t += G) {
;                 int base, n1, S1, lS;
;                 if (t < 512) { base = (t >> 6) * 2048; n1 = t & 63; S1 = 64; lS = 11; } else { const int tt = t - 512; base = M_PROMPT + (tt >> 8) * 8192; n1 = tt & 255; S1 = 256; lS = 13; }
;                 __syncthreads();
;                 if (tid < 32) TW2[tid] = TWT[(t < 512 ? TW_2A : TW_2B) + n1 * 32 + tid];
;                 { bf16_t hv[32];
; #pragma unroll
;                 for (int n2 = 0; n2 < 32; ++n2) hv[n2] = H[SEG_F + (size_t)(base + n1 + S1 * n2) * LDF + tid];
.LBB0_306:
	s_or_b64 exec, exec, s[8:9]
	v_readlane_b32 s2, v253, 13
	v_readlane_b32 s3, v253, 14
	s_andn2_b64 vcc, exec, s[2:3]
	s_nop 0
	v_cndmask_b32_e64 v0, 0, 1, s[2:3]
	v_cmp_ne_u32_e64 s[0:1], 1, v0
	s_nop 1
	v_writelane_b32 v255, s0, 13
	s_nop 1
	v_writelane_b32 v255, s1, 14
	s_cbranch_vccnz .LBB0_316
	s_cmp_eq_u32 s101, 1
	s_cbranch_scc1 .LBB0_316
.Lp2_fft1:
	s_waitcnt lgkmcnt(0)
	s_add_u32 s0, s6, 0x4dd7e000
	s_addc_u32 s1, s7, 0
	v_writelane_b32 v255, s0, 15
	v_readlane_b32 s2, v254, 24
	v_lshl_add_u64 v[0:1], v[48:49], 1, s[6:7]
	v_writelane_b32 v255, s1, 16
	v_cmp_gt_i32_e64 s[0:1], 32, v48
	v_lshl_add_u32 v120, v48, 3, s2
	s_mov_b64 s[2:3], 0x10d2a000
	v_writelane_b32 v255, s0, 17
	v_lshl_add_u64 v[4:5], v[0:1], 0, s[2:3]
	v_lshl_add_u64 v[0:1], v[48:49], 3, s[6:7]
	s_mov_b64 s[2:3], 0x40d2a000
	v_writelane_b32 v255, s1, 18
	v_lshl_add_u64 v[6:7], v[0:1], 0, s[2:3]
	v_readlane_b32 s72, v253, 49
	v_readlane_b32 s2, v253, 7
	v_readlane_b32 s3, v253, 8
	s_branch .LBB0_309

; __global__ void __launch_bounds__(512, 2) fwd_megakernel(Params p_) {
;     ...
;                     ZB[(size_t)(base + k2 * S1 + n1) * 512 + tid] = (f32x2){re[i2] * w.x - im[i2] * w.y, re[i2] * w.y + im[i2] * w.x}; } }
;             }
;             __syncthreads();
;             {
.LBB0_316:
	s_cmp_eq_u32 s101, 3
	s_cbranch_scc0 .Lp2_c316
	v_readlane_b32 s2, v253, 15
	v_readlane_b32 s3, v253, 16
	s_nop 1
	v_cndmask_b32_e64 v0, 0, 1, s[2:3]
	v_cmp_ne_u32_e64 s[8:9], 1, v0
	s_branch .LBB0_504

; __global__ void __launch_bounds__(512, 2) fwd_megakernel(Params p_) {
;     ...
;                 }
;             }
;             {
;                 for (size_t e = gt; e < (size_t)M_TOK * 2; e += NGT) STATS[e] = 0.f;
.LBB0_504:
	s_cmp_eq_u32 s101, 1
	s_cbranch_scc0 .Lp2_cont
	s_mov_b32 s101, 3
	s_branch .Lp2_fft1
